# EpiResid epilogues (out-proj, FFN-down): the 4 residual loads of each row issued together with one wait (8 round trips instead of 32)
# speedup vs baseline: 1.0124x; 1.0059x over previous
; __device__ __forceinline__ unsigned cvt_pk_bf16(float lo, float hi) { const cvt2_f32x2 v = {lo, hi}; const cvt2_bf16x2 r = __builtin_convertvector(v, cvt2_bf16x2); return __builtin_bit_cast(unsigned, r); }
;     __device__ __forceinline__ void operator()(const f32x4 (&acc)[2][2][4][2], const Unit& u, int wr, int wc, int fr, int fq) const {
;     ...
;         const int row0 = u.pm * BM + wr * 64 + fr, col0 = u.pn * BM + wc * 32 + 4 * fq;
; #pragma unroll
;         for (int ai = 0; ai < 2; ++ai)
; #pragma unroll
;             for (int m = 0; m < 4; ++m) {
;                 const int row = row0 + ai * HALF + m * 16;
;                 const size_t off = (size_t)row * 2048 + col0;
;                 float s = 0.f;
; #pragma unroll
;                 for (int bj = 0; bj < 2; ++bj)
; #pragma unroll
;                     for (int n = 0; n < 2; ++n) {
;                         const f32x4 b = *(const f32x4*)(base + off + bj * HALF + n * 16);
;                         const f32x4 v = b + acc[ai][bj][m][n];
;                         *(f32x4*)(out + off + bj * HALF + n * 16) = v;
;                         if (xb) { u32x2 w; w.x = cvt_pk_bf16(v[0], v[1]); w.y = cvt_pk_bf16(v[2], v[3]); *(u32x2*)(xb + off + bj * HALF + n * 16) = w; }
.LBB0_300:
	v_lshl_add_u32 v138, s35, 8, v146
	v_lshl_or_b32 v136, s34, 8, v148
	v_ashrrev_i32_e32 v139, 31, v138
	v_ashrrev_i32_e32 v137, 31, v136
	v_lshlrev_b64 v[140:141], 11, v[138:139]
	v_lshl_add_u64 v[142:143], v[140:141], 0, v[136:137]
	v_lshlrev_b64 v[144:145], 2, v[142:143]
	v_lshl_add_u64 v[140:141], s[12:13], 0, v[144:145]
	global_load_dwordx4 v[150:153], v[140:141], off
	global_load_dwordx4 v[156:159], v[140:141], off offset:64
	global_load_dwordx4 v[160:163], v[140:141], off offset:512
	global_load_dwordx4 v[164:167], v[140:141], off offset:576
	v_cndmask_b32_e64 v154, 0, 1, s[44:45]
	v_cmp_ne_u32_e64 s[8:9], 1, v154
	s_andn2_b64 vcc, exec, s[44:45]
	v_lshl_add_u64 v[144:145], s[26:27], 0, v[144:145]
	v_lshl_add_u64 v[142:143], v[142:143], 1, s[18:19]
	v_readlane_b32 s84, v255, 3
	s_movk_i32 s86, 0x4000
	s_movk_i32 s93, 0x60
	s_mov_b32 s91, 0x6c000
	s_waitcnt vmcnt(0)
	v_pk_add_f32 v[128:129], v[128:129], v[152:153]
	v_pk_add_f32 v[126:127], v[126:127], v[150:151]
	global_store_dwordx4 v[144:145], v[126:129], off
	s_cbranch_vccnz .LBB0_302
	v_cvt_pk_bf16_f32 v150, v126, v127
	v_cvt_pk_bf16_f32 v151, v128, v129
	global_store_dwordx2 v[142:143], v[150:151], off
.LBB0_302:
	s_and_b64 vcc, exec, s[8:9]
	v_pk_add_f32 v[124:125], v[124:125], v[158:159]
	v_pk_add_f32 v[122:123], v[122:123], v[156:157]
	global_store_dwordx4 v[144:145], v[122:125], off offset:64
	s_cbranch_vccnz .LBB0_304

; __device__ __forceinline__ unsigned cvt_pk_bf16(float lo, float hi) { const cvt2_f32x2 v = {lo, hi}; const cvt2_bf16x2 r = __builtin_convertvector(v, cvt2_bf16x2); return __builtin_bit_cast(unsigned, r); }
;     __device__ __forceinline__ void operator()(const f32x4 (&acc)[2][2][4][2], const Unit& u, int wr, int wc, int fr, int fq) const {
;     ...
;                 for (int bj = 0; bj < 2; ++bj)
; #pragma unroll
;                     for (int n = 0; n < 2; ++n) {
;                         const f32x4 b = *(const f32x4*)(base + off + bj * HALF + n * 16);
;                         const f32x4 v = b + acc[ai][bj][m][n];
;                         *(f32x4*)(out + off + bj * HALF + n * 16) = v;
;                         if (xb) { u32x2 w; w.x = cvt_pk_bf16(v[0], v[1]); w.y = cvt_pk_bf16(v[2], v[3]); *(u32x2*)(xb + off + bj * HALF + n * 16) = w; }
	v_cvt_pk_bf16_f32 v156, v122, v123
	v_cvt_pk_bf16_f32 v157, v124, v125
	global_store_dwordx2 v[142:143], v[156:157], off offset:32
.LBB0_304:
	s_and_b64 vcc, exec, s[8:9]
	v_pk_add_f32 v[120:121], v[120:121], v[162:163]
	v_pk_add_f32 v[118:119], v[118:119], v[160:161]
	global_store_dwordx4 v[144:145], v[118:121], off offset:512
	s_cbranch_vccnz .LBB0_306

; __device__ __forceinline__ unsigned cvt_pk_bf16(float lo, float hi) { const cvt2_f32x2 v = {lo, hi}; const cvt2_bf16x2 r = __builtin_convertvector(v, cvt2_bf16x2); return __builtin_bit_cast(unsigned, r); }
;     __device__ __forceinline__ void operator()(const f32x4 (&acc)[2][2][4][2], const Unit& u, int wr, int wc, int fr, int fq) const {
;     ...
;                 for (int bj = 0; bj < 2; ++bj)
; #pragma unroll
;                     for (int n = 0; n < 2; ++n) {
;                         const f32x4 b = *(const f32x4*)(base + off + bj * HALF + n * 16);
;                         const f32x4 v = b + acc[ai][bj][m][n];
;                         *(f32x4*)(out + off + bj * HALF + n * 16) = v;
;                         if (xb) { u32x2 w; w.x = cvt_pk_bf16(v[0], v[1]); w.y = cvt_pk_bf16(v[2], v[3]); *(u32x2*)(xb + off + bj * HALF + n * 16) = w; }
	v_cvt_pk_bf16_f32 v160, v118, v119
	v_cvt_pk_bf16_f32 v161, v120, v121
	global_store_dwordx2 v[142:143], v[160:161], off offset:256
.LBB0_306:
	s_and_b64 vcc, exec, s[8:9]
	v_pk_add_f32 v[116:117], v[116:117], v[166:167]
	v_pk_add_f32 v[114:115], v[114:115], v[164:165]
	global_store_dwordx4 v[144:145], v[114:117], off offset:576
	s_cbranch_vccnz .LBB0_308

; __device__ __forceinline__ unsigned cvt_pk_bf16(float lo, float hi) { const cvt2_f32x2 v = {lo, hi}; const cvt2_bf16x2 r = __builtin_convertvector(v, cvt2_bf16x2); return __builtin_bit_cast(unsigned, r); }
;     __device__ __forceinline__ void operator()(const f32x4 (&acc)[2][2][4][2], const Unit& u, int wr, int wc, int fr, int fq) const {
;     ...
;                         if (xb) { u32x2 w; w.x = cvt_pk_bf16(v[0], v[1]); w.y = cvt_pk_bf16(v[2], v[3]); *(u32x2*)(xb + off + bj * HALF + n * 16) = w; }
	v_cvt_pk_bf16_f32 v140, v114, v115
	v_cvt_pk_bf16_f32 v141, v116, v117
	global_store_dwordx2 v[142:143], v[140:141], off offset:288

; __device__ __forceinline__ unsigned cvt_pk_bf16(float lo, float hi) { const cvt2_f32x2 v = {lo, hi}; const cvt2_bf16x2 r = __builtin_convertvector(v, cvt2_bf16x2); return __builtin_bit_cast(unsigned, r); }
;     __device__ __forceinline__ void operator()(const f32x4 (&acc)[2][2][4][2], const Unit& u, int wr, int wc, int fr, int fq) const {
;     ...
;                 const int row = row0 + ai * HALF + m * 16;
;                 const size_t off = (size_t)row * 2048 + col0;
;                 float s = 0.f;
; #pragma unroll
;                 for (int bj = 0; bj < 2; ++bj)
; #pragma unroll
;                     for (int n = 0; n < 2; ++n) {
;                         const f32x4 b = *(const f32x4*)(base + off + bj * HALF + n * 16);
;                         const f32x4 v = b + acc[ai][bj][m][n];
;                         *(f32x4*)(out + off + bj * HALF + n * 16) = v;
;                         if (xb) { u32x2 w; w.x = cvt_pk_bf16(v[0], v[1]); w.y = cvt_pk_bf16(v[2], v[3]); *(u32x2*)(xb + off + bj * HALF + n * 16) = w; }
.LBB0_312:
	v_or_b32_e32 v114, 16, v138
	s_waitcnt lgkmcnt(0)
	v_ashrrev_i32_e32 v115, 31, v114
	v_lshlrev_b64 v[116:117], 11, v[114:115]
	v_lshl_add_u64 v[116:117], v[116:117], 0, v[136:137]
	v_lshlrev_b64 v[120:121], 2, v[116:117]
	v_lshl_add_u64 v[118:119], s[12:13], 0, v[120:121]
	global_load_dwordx4 v[122:125], v[118:119], off
	global_load_dwordx4 v[156:159], v[118:119], off offset:64
	global_load_dwordx4 v[160:163], v[118:119], off offset:512
	global_load_dwordx4 v[164:167], v[118:119], off offset:576
	s_and_b64 vcc, exec, s[8:9]
	v_lshl_add_u64 v[120:121], s[26:27], 0, v[120:121]
	v_lshl_add_u64 v[116:117], v[116:117], 1, s[18:19]
	s_waitcnt vmcnt(0)
	v_pk_add_f32 v[112:113], v[112:113], v[124:125]
	v_pk_add_f32 v[110:111], v[110:111], v[122:123]
	global_store_dwordx4 v[120:121], v[110:113], off
	s_cbranch_vccnz .LBB0_314
	v_cvt_pk_bf16_f32 v122, v110, v111
	v_cvt_pk_bf16_f32 v123, v112, v113
	global_store_dwordx2 v[116:117], v[122:123], off
.LBB0_314:
	s_and_b64 vcc, exec, s[8:9]
	v_pk_add_f32 v[108:109], v[108:109], v[158:159]
	v_pk_add_f32 v[106:107], v[106:107], v[156:157]
	global_store_dwordx4 v[120:121], v[106:109], off offset:64
	s_cbranch_vccnz .LBB0_316

; __device__ __forceinline__ unsigned cvt_pk_bf16(float lo, float hi) { const cvt2_f32x2 v = {lo, hi}; const cvt2_bf16x2 r = __builtin_convertvector(v, cvt2_bf16x2); return __builtin_bit_cast(unsigned, r); }
;     __device__ __forceinline__ void operator()(const f32x4 (&acc)[2][2][4][2], const Unit& u, int wr, int wc, int fr, int fq) const {
;     ...
;                 for (int bj = 0; bj < 2; ++bj)
; #pragma unroll
;                     for (int n = 0; n < 2; ++n) {
;                         const f32x4 b = *(const f32x4*)(base + off + bj * HALF + n * 16);
;                         const f32x4 v = b + acc[ai][bj][m][n];
;                         *(f32x4*)(out + off + bj * HALF + n * 16) = v;
;                         if (xb) { u32x2 w; w.x = cvt_pk_bf16(v[0], v[1]); w.y = cvt_pk_bf16(v[2], v[3]); *(u32x2*)(xb + off + bj * HALF + n * 16) = w; }
	v_cvt_pk_bf16_f32 v156, v106, v107
	v_cvt_pk_bf16_f32 v157, v108, v109
	global_store_dwordx2 v[116:117], v[156:157], off offset:32
.LBB0_316:
	s_and_b64 vcc, exec, s[8:9]
	v_pk_add_f32 v[104:105], v[104:105], v[162:163]
	v_pk_add_f32 v[102:103], v[102:103], v[160:161]
	global_store_dwordx4 v[120:121], v[102:105], off offset:512
	s_cbranch_vccnz .LBB0_318

; __device__ __forceinline__ unsigned cvt_pk_bf16(float lo, float hi) { const cvt2_f32x2 v = {lo, hi}; const cvt2_bf16x2 r = __builtin_convertvector(v, cvt2_bf16x2); return __builtin_bit_cast(unsigned, r); }
;     __device__ __forceinline__ void operator()(const f32x4 (&acc)[2][2][4][2], const Unit& u, int wr, int wc, int fr, int fq) const {
;     ...
;                 for (int bj = 0; bj < 2; ++bj)
; #pragma unroll
;                     for (int n = 0; n < 2; ++n) {
;                         const f32x4 b = *(const f32x4*)(base + off + bj * HALF + n * 16);
;                         const f32x4 v = b + acc[ai][bj][m][n];
;                         *(f32x4*)(out + off + bj * HALF + n * 16) = v;
;                         if (xb) { u32x2 w; w.x = cvt_pk_bf16(v[0], v[1]); w.y = cvt_pk_bf16(v[2], v[3]); *(u32x2*)(xb + off + bj * HALF + n * 16) = w; }
	v_cvt_pk_bf16_f32 v160, v102, v103
	v_cvt_pk_bf16_f32 v161, v104, v105
	global_store_dwordx2 v[116:117], v[160:161], off offset:256
.LBB0_318:
	s_and_b64 vcc, exec, s[8:9]
	v_pk_add_f32 v[100:101], v[100:101], v[166:167]
	v_pk_add_f32 v[98:99], v[98:99], v[164:165]
	global_store_dwordx4 v[120:121], v[98:101], off offset:576
	s_cbranch_vccnz .LBB0_320

; __device__ __forceinline__ unsigned cvt_pk_bf16(float lo, float hi) { const cvt2_f32x2 v = {lo, hi}; const cvt2_bf16x2 r = __builtin_convertvector(v, cvt2_bf16x2); return __builtin_bit_cast(unsigned, r); }
;     __device__ __forceinline__ void operator()(const f32x4 (&acc)[2][2][4][2], const Unit& u, int wr, int wc, int fr, int fq) const {
;     ...
;                         if (xb) { u32x2 w; w.x = cvt_pk_bf16(v[0], v[1]); w.y = cvt_pk_bf16(v[2], v[3]); *(u32x2*)(xb + off + bj * HALF + n * 16) = w; }
	v_cvt_pk_bf16_f32 v118, v98, v99
	v_cvt_pk_bf16_f32 v119, v100, v101
	global_store_dwordx2 v[116:117], v[118:119], off offset:288

; __device__ __forceinline__ unsigned cvt_pk_bf16(float lo, float hi) { const cvt2_f32x2 v = {lo, hi}; const cvt2_bf16x2 r = __builtin_convertvector(v, cvt2_bf16x2); return __builtin_bit_cast(unsigned, r); }
;     __device__ __forceinline__ void operator()(const f32x4 (&acc)[2][2][4][2], const Unit& u, int wr, int wc, int fr, int fq) const {
;     ...
;                 const int row = row0 + ai * HALF + m * 16;
;                 const size_t off = (size_t)row * 2048 + col0;
;                 float s = 0.f;
; #pragma unroll
;                 for (int bj = 0; bj < 2; ++bj)
; #pragma unroll
;                     for (int n = 0; n < 2; ++n) {
;                         const f32x4 b = *(const f32x4*)(base + off + bj * HALF + n * 16);
;                         const f32x4 v = b + acc[ai][bj][m][n];
;                         *(f32x4*)(out + off + bj * HALF + n * 16) = v;
;                         if (xb) { u32x2 w; w.x = cvt_pk_bf16(v[0], v[1]); w.y = cvt_pk_bf16(v[2], v[3]); *(u32x2*)(xb + off + bj * HALF + n * 16) = w; }
.LBB0_324:
	v_or_b32_e32 v98, 32, v138
	s_waitcnt lgkmcnt(0)
	v_ashrrev_i32_e32 v99, 31, v98
	v_lshlrev_b64 v[100:101], 11, v[98:99]
	v_lshl_add_u64 v[100:101], v[100:101], 0, v[136:137]
	v_lshlrev_b64 v[104:105], 2, v[100:101]
	v_lshl_add_u64 v[102:103], s[12:13], 0, v[104:105]
	global_load_dwordx4 v[106:109], v[102:103], off
	global_load_dwordx4 v[156:159], v[102:103], off offset:64
	global_load_dwordx4 v[160:163], v[102:103], off offset:512
	global_load_dwordx4 v[164:167], v[102:103], off offset:576
	s_and_b64 vcc, exec, s[8:9]
	v_lshl_add_u64 v[104:105], s[26:27], 0, v[104:105]
	v_lshl_add_u64 v[100:101], v[100:101], 1, s[18:19]
	s_waitcnt vmcnt(0)
	v_pk_add_f32 v[96:97], v[96:97], v[108:109]
	v_pk_add_f32 v[94:95], v[94:95], v[106:107]
	global_store_dwordx4 v[104:105], v[94:97], off
	s_cbranch_vccnz .LBB0_326
	v_cvt_pk_bf16_f32 v106, v94, v95
	v_cvt_pk_bf16_f32 v107, v96, v97
	global_store_dwordx2 v[100:101], v[106:107], off
.LBB0_326:
	s_and_b64 vcc, exec, s[8:9]
	v_pk_add_f32 v[92:93], v[92:93], v[158:159]
	v_pk_add_f32 v[90:91], v[90:91], v[156:157]
	global_store_dwordx4 v[104:105], v[90:93], off offset:64
	s_cbranch_vccnz .LBB0_328

; __device__ __forceinline__ unsigned cvt_pk_bf16(float lo, float hi) { const cvt2_f32x2 v = {lo, hi}; const cvt2_bf16x2 r = __builtin_convertvector(v, cvt2_bf16x2); return __builtin_bit_cast(unsigned, r); }
;     __device__ __forceinline__ void operator()(const f32x4 (&acc)[2][2][4][2], const Unit& u, int wr, int wc, int fr, int fq) const {
;     ...
;                 for (int bj = 0; bj < 2; ++bj)
; #pragma unroll
;                     for (int n = 0; n < 2; ++n) {
;                         const f32x4 b = *(const f32x4*)(base + off + bj * HALF + n * 16);
;                         const f32x4 v = b + acc[ai][bj][m][n];
;                         *(f32x4*)(out + off + bj * HALF + n * 16) = v;
;                         if (xb) { u32x2 w; w.x = cvt_pk_bf16(v[0], v[1]); w.y = cvt_pk_bf16(v[2], v[3]); *(u32x2*)(xb + off + bj * HALF + n * 16) = w; }
	v_cvt_pk_bf16_f32 v156, v90, v91
	v_cvt_pk_bf16_f32 v157, v92, v93
	global_store_dwordx2 v[100:101], v[156:157], off offset:32
.LBB0_328:
	s_and_b64 vcc, exec, s[8:9]
	v_pk_add_f32 v[88:89], v[88:89], v[162:163]
	v_pk_add_f32 v[86:87], v[86:87], v[160:161]
	global_store_dwordx4 v[104:105], v[86:89], off offset:512
	s_cbranch_vccnz .LBB0_330

; __device__ __forceinline__ unsigned cvt_pk_bf16(float lo, float hi) { const cvt2_f32x2 v = {lo, hi}; const cvt2_bf16x2 r = __builtin_convertvector(v, cvt2_bf16x2); return __builtin_bit_cast(unsigned, r); }
;     __device__ __forceinline__ void operator()(const f32x4 (&acc)[2][2][4][2], const Unit& u, int wr, int wc, int fr, int fq) const {
;     ...
;                 for (int bj = 0; bj < 2; ++bj)
; #pragma unroll
;                     for (int n = 0; n < 2; ++n) {
;                         const f32x4 b = *(const f32x4*)(base + off + bj * HALF + n * 16);
;                         const f32x4 v = b + acc[ai][bj][m][n];
;                         *(f32x4*)(out + off + bj * HALF + n * 16) = v;
;                         if (xb) { u32x2 w; w.x = cvt_pk_bf16(v[0], v[1]); w.y = cvt_pk_bf16(v[2], v[3]); *(u32x2*)(xb + off + bj * HALF + n * 16) = w; }
	v_cvt_pk_bf16_f32 v160, v86, v87
	v_cvt_pk_bf16_f32 v161, v88, v89
	global_store_dwordx2 v[100:101], v[160:161], off offset:256
.LBB0_330:
	s_and_b64 vcc, exec, s[8:9]
	v_pk_add_f32 v[84:85], v[84:85], v[166:167]
	v_pk_add_f32 v[82:83], v[82:83], v[164:165]
	global_store_dwordx4 v[104:105], v[82:85], off offset:576
	s_cbranch_vccnz .LBB0_332

; __device__ __forceinline__ unsigned cvt_pk_bf16(float lo, float hi) { const cvt2_f32x2 v = {lo, hi}; const cvt2_bf16x2 r = __builtin_convertvector(v, cvt2_bf16x2); return __builtin_bit_cast(unsigned, r); }
;     __device__ __forceinline__ void operator()(const f32x4 (&acc)[2][2][4][2], const Unit& u, int wr, int wc, int fr, int fq) const {
;     ...
;                         if (xb) { u32x2 w; w.x = cvt_pk_bf16(v[0], v[1]); w.y = cvt_pk_bf16(v[2], v[3]); *(u32x2*)(xb + off + bj * HALF + n * 16) = w; }
	v_cvt_pk_bf16_f32 v102, v82, v83
	v_cvt_pk_bf16_f32 v103, v84, v85
	global_store_dwordx2 v[100:101], v[102:103], off offset:288

; __device__ __forceinline__ unsigned cvt_pk_bf16(float lo, float hi) { const cvt2_f32x2 v = {lo, hi}; const cvt2_bf16x2 r = __builtin_convertvector(v, cvt2_bf16x2); return __builtin_bit_cast(unsigned, r); }
;     __device__ __forceinline__ void operator()(const f32x4 (&acc)[2][2][4][2], const Unit& u, int wr, int wc, int fr, int fq) const {
;     ...
;                 const int row = row0 + ai * HALF + m * 16;
;                 const size_t off = (size_t)row * 2048 + col0;
;                 float s = 0.f;
; #pragma unroll
;                 for (int bj = 0; bj < 2; ++bj)
; #pragma unroll
;                     for (int n = 0; n < 2; ++n) {
;                         const f32x4 b = *(const f32x4*)(base + off + bj * HALF + n * 16);
;                         const f32x4 v = b + acc[ai][bj][m][n];
;                         *(f32x4*)(out + off + bj * HALF + n * 16) = v;
;                         if (xb) { u32x2 w; w.x = cvt_pk_bf16(v[0], v[1]); w.y = cvt_pk_bf16(v[2], v[3]); *(u32x2*)(xb + off + bj * HALF + n * 16) = w; }
.LBB0_336:
	v_or_b32_e32 v82, 48, v138
	s_waitcnt lgkmcnt(0)
	v_ashrrev_i32_e32 v83, 31, v82
	v_lshlrev_b64 v[84:85], 11, v[82:83]
	v_lshl_add_u64 v[84:85], v[84:85], 0, v[136:137]
	v_lshlrev_b64 v[88:89], 2, v[84:85]
	v_lshl_add_u64 v[86:87], s[12:13], 0, v[88:89]
	global_load_dwordx4 v[90:93], v[86:87], off
	global_load_dwordx4 v[156:159], v[86:87], off offset:64
	global_load_dwordx4 v[160:163], v[86:87], off offset:512
	global_load_dwordx4 v[164:167], v[86:87], off offset:576
	s_and_b64 vcc, exec, s[8:9]
	v_lshl_add_u64 v[88:89], s[26:27], 0, v[88:89]
	v_lshl_add_u64 v[84:85], v[84:85], 1, s[18:19]
	s_waitcnt vmcnt(0)
	v_pk_add_f32 v[80:81], v[80:81], v[92:93]
	v_pk_add_f32 v[78:79], v[78:79], v[90:91]
	global_store_dwordx4 v[88:89], v[78:81], off
	s_cbranch_vccnz .LBB0_338
	v_cvt_pk_bf16_f32 v90, v78, v79
	v_cvt_pk_bf16_f32 v91, v80, v81
	global_store_dwordx2 v[84:85], v[90:91], off
.LBB0_338:
	s_and_b64 vcc, exec, s[8:9]
	v_pk_add_f32 v[76:77], v[76:77], v[158:159]
	v_pk_add_f32 v[74:75], v[74:75], v[156:157]
	global_store_dwordx4 v[88:89], v[74:77], off offset:64
	s_cbranch_vccnz .LBB0_340

; __device__ __forceinline__ unsigned cvt_pk_bf16(float lo, float hi) { const cvt2_f32x2 v = {lo, hi}; const cvt2_bf16x2 r = __builtin_convertvector(v, cvt2_bf16x2); return __builtin_bit_cast(unsigned, r); }
;     __device__ __forceinline__ void operator()(const f32x4 (&acc)[2][2][4][2], const Unit& u, int wr, int wc, int fr, int fq) const {
;     ...
;                 for (int bj = 0; bj < 2; ++bj)
; #pragma unroll
;                     for (int n = 0; n < 2; ++n) {
;                         const f32x4 b = *(const f32x4*)(base + off + bj * HALF + n * 16);
;                         const f32x4 v = b + acc[ai][bj][m][n];
;                         *(f32x4*)(out + off + bj * HALF + n * 16) = v;
;                         if (xb) { u32x2 w; w.x = cvt_pk_bf16(v[0], v[1]); w.y = cvt_pk_bf16(v[2], v[3]); *(u32x2*)(xb + off + bj * HALF + n * 16) = w; }
	v_cvt_pk_bf16_f32 v156, v74, v75
	v_cvt_pk_bf16_f32 v157, v76, v77
	global_store_dwordx2 v[84:85], v[156:157], off offset:32
.LBB0_340:
	s_and_b64 vcc, exec, s[8:9]
	v_pk_add_f32 v[72:73], v[72:73], v[162:163]
	v_pk_add_f32 v[70:71], v[70:71], v[160:161]
	global_store_dwordx4 v[88:89], v[70:73], off offset:512
	s_cbranch_vccnz .LBB0_342

; __device__ __forceinline__ unsigned cvt_pk_bf16(float lo, float hi) { const cvt2_f32x2 v = {lo, hi}; const cvt2_bf16x2 r = __builtin_convertvector(v, cvt2_bf16x2); return __builtin_bit_cast(unsigned, r); }
;     __device__ __forceinline__ void operator()(const f32x4 (&acc)[2][2][4][2], const Unit& u, int wr, int wc, int fr, int fq) const {
;     ...
;                 for (int bj = 0; bj < 2; ++bj)
; #pragma unroll
;                     for (int n = 0; n < 2; ++n) {
;                         const f32x4 b = *(const f32x4*)(base + off + bj * HALF + n * 16);
;                         const f32x4 v = b + acc[ai][bj][m][n];
;                         *(f32x4*)(out + off + bj * HALF + n * 16) = v;
;                         if (xb) { u32x2 w; w.x = cvt_pk_bf16(v[0], v[1]); w.y = cvt_pk_bf16(v[2], v[3]); *(u32x2*)(xb + off + bj * HALF + n * 16) = w; }
	v_cvt_pk_bf16_f32 v160, v70, v71
	v_cvt_pk_bf16_f32 v161, v72, v73
	global_store_dwordx2 v[84:85], v[160:161], off offset:256
.LBB0_342:
	s_and_b64 vcc, exec, s[8:9]
	v_pk_add_f32 v[68:69], v[68:69], v[166:167]
	v_pk_add_f32 v[66:67], v[66:67], v[164:165]
	global_store_dwordx4 v[88:89], v[66:69], off offset:576
	s_cbranch_vccnz .LBB0_344

; __device__ __forceinline__ unsigned cvt_pk_bf16(float lo, float hi) { const cvt2_f32x2 v = {lo, hi}; const cvt2_bf16x2 r = __builtin_convertvector(v, cvt2_bf16x2); return __builtin_bit_cast(unsigned, r); }
;     __device__ __forceinline__ void operator()(const f32x4 (&acc)[2][2][4][2], const Unit& u, int wr, int wc, int fr, int fq) const {
;     ...
;                         if (xb) { u32x2 w; w.x = cvt_pk_bf16(v[0], v[1]); w.y = cvt_pk_bf16(v[2], v[3]); *(u32x2*)(xb + off + bj * HALF + n * 16) = w; }
	v_cvt_pk_bf16_f32 v86, v66, v67
	v_cvt_pk_bf16_f32 v87, v68, v69
	global_store_dwordx2 v[84:85], v[86:87], off offset:288

; __device__ __forceinline__ unsigned cvt_pk_bf16(float lo, float hi) { const cvt2_f32x2 v = {lo, hi}; const cvt2_bf16x2 r = __builtin_convertvector(v, cvt2_bf16x2); return __builtin_bit_cast(unsigned, r); }
;     __device__ __forceinline__ void operator()(const f32x4 (&acc)[2][2][4][2], const Unit& u, int wr, int wc, int fr, int fq) const {
;     ...
;                 const int row = row0 + ai * HALF + m * 16;
;                 const size_t off = (size_t)row * 2048 + col0;
;                 float s = 0.f;
; #pragma unroll
;                 for (int bj = 0; bj < 2; ++bj)
; #pragma unroll
;                     for (int n = 0; n < 2; ++n) {
;                         const f32x4 b = *(const f32x4*)(base + off + bj * HALF + n * 16);
;                         const f32x4 v = b + acc[ai][bj][m][n];
;                         *(f32x4*)(out + off + bj * HALF + n * 16) = v;
;                         if (xb) { u32x2 w; w.x = cvt_pk_bf16(v[0], v[1]); w.y = cvt_pk_bf16(v[2], v[3]); *(u32x2*)(xb + off + bj * HALF + n * 16) = w; }
.LBB0_348:
	v_add_u32_e32 v66, 0x80, v138
	s_waitcnt lgkmcnt(0)
	v_ashrrev_i32_e32 v67, 31, v66
	v_lshlrev_b64 v[68:69], 11, v[66:67]
	v_lshl_add_u64 v[68:69], v[68:69], 0, v[136:137]
	v_lshlrev_b64 v[72:73], 2, v[68:69]
	v_lshl_add_u64 v[70:71], s[12:13], 0, v[72:73]
	global_load_dwordx4 v[74:77], v[70:71], off
	global_load_dwordx4 v[156:159], v[70:71], off offset:64
	global_load_dwordx4 v[160:163], v[70:71], off offset:512
	global_load_dwordx4 v[164:167], v[70:71], off offset:576
	s_and_b64 vcc, exec, s[8:9]
	v_lshl_add_u64 v[72:73], s[26:27], 0, v[72:73]
	v_lshl_add_u64 v[68:69], v[68:69], 1, s[18:19]
	s_waitcnt vmcnt(0)
	v_pk_add_f32 v[64:65], v[64:65], v[76:77]
	v_pk_add_f32 v[62:63], v[62:63], v[74:75]
	global_store_dwordx4 v[72:73], v[62:65], off
	s_cbranch_vccnz .LBB0_350
	v_cvt_pk_bf16_f32 v74, v62, v63
	v_cvt_pk_bf16_f32 v75, v64, v65
	global_store_dwordx2 v[68:69], v[74:75], off
.LBB0_350:
	s_and_b64 vcc, exec, s[8:9]
	v_pk_add_f32 v[60:61], v[60:61], v[158:159]
	v_pk_add_f32 v[58:59], v[58:59], v[156:157]
	global_store_dwordx4 v[72:73], v[58:61], off offset:64
	s_cbranch_vccnz .LBB0_352

; __device__ __forceinline__ unsigned cvt_pk_bf16(float lo, float hi) { const cvt2_f32x2 v = {lo, hi}; const cvt2_bf16x2 r = __builtin_convertvector(v, cvt2_bf16x2); return __builtin_bit_cast(unsigned, r); }
;     __device__ __forceinline__ void operator()(const f32x4 (&acc)[2][2][4][2], const Unit& u, int wr, int wc, int fr, int fq) const {
;     ...
;                 for (int bj = 0; bj < 2; ++bj)
; #pragma unroll
;                     for (int n = 0; n < 2; ++n) {
;                         const f32x4 b = *(const f32x4*)(base + off + bj * HALF + n * 16);
;                         const f32x4 v = b + acc[ai][bj][m][n];
;                         *(f32x4*)(out + off + bj * HALF + n * 16) = v;
;                         if (xb) { u32x2 w; w.x = cvt_pk_bf16(v[0], v[1]); w.y = cvt_pk_bf16(v[2], v[3]); *(u32x2*)(xb + off + bj * HALF + n * 16) = w; }
	v_cvt_pk_bf16_f32 v156, v58, v59
	v_cvt_pk_bf16_f32 v157, v60, v61
	global_store_dwordx2 v[68:69], v[156:157], off offset:32
.LBB0_352:
	s_and_b64 vcc, exec, s[8:9]
	v_pk_add_f32 v[56:57], v[56:57], v[162:163]
	v_pk_add_f32 v[54:55], v[54:55], v[160:161]
	global_store_dwordx4 v[72:73], v[54:57], off offset:512
	s_cbranch_vccnz .LBB0_354

; __device__ __forceinline__ unsigned cvt_pk_bf16(float lo, float hi) { const cvt2_f32x2 v = {lo, hi}; const cvt2_bf16x2 r = __builtin_convertvector(v, cvt2_bf16x2); return __builtin_bit_cast(unsigned, r); }
;     __device__ __forceinline__ void operator()(const f32x4 (&acc)[2][2][4][2], const Unit& u, int wr, int wc, int fr, int fq) const {
;     ...
;                 for (int bj = 0; bj < 2; ++bj)
; #pragma unroll
;                     for (int n = 0; n < 2; ++n) {
;                         const f32x4 b = *(const f32x4*)(base + off + bj * HALF + n * 16);
;                         const f32x4 v = b + acc[ai][bj][m][n];
;                         *(f32x4*)(out + off + bj * HALF + n * 16) = v;
;                         if (xb) { u32x2 w; w.x = cvt_pk_bf16(v[0], v[1]); w.y = cvt_pk_bf16(v[2], v[3]); *(u32x2*)(xb + off + bj * HALF + n * 16) = w; }
	v_cvt_pk_bf16_f32 v160, v54, v55
	v_cvt_pk_bf16_f32 v161, v56, v57
	global_store_dwordx2 v[68:69], v[160:161], off offset:256
.LBB0_354:
	s_and_b64 vcc, exec, s[8:9]
	v_pk_add_f32 v[52:53], v[52:53], v[166:167]
	v_pk_add_f32 v[50:51], v[50:51], v[164:165]
	global_store_dwordx4 v[72:73], v[50:53], off offset:576
	s_cbranch_vccnz .LBB0_356

; __device__ __forceinline__ unsigned cvt_pk_bf16(float lo, float hi) { const cvt2_f32x2 v = {lo, hi}; const cvt2_bf16x2 r = __builtin_convertvector(v, cvt2_bf16x2); return __builtin_bit_cast(unsigned, r); }
;     __device__ __forceinline__ void operator()(const f32x4 (&acc)[2][2][4][2], const Unit& u, int wr, int wc, int fr, int fq) const {
;     ...
;                         if (xb) { u32x2 w; w.x = cvt_pk_bf16(v[0], v[1]); w.y = cvt_pk_bf16(v[2], v[3]); *(u32x2*)(xb + off + bj * HALF + n * 16) = w; }
	v_cvt_pk_bf16_f32 v70, v50, v51
	v_cvt_pk_bf16_f32 v71, v52, v53
	global_store_dwordx2 v[68:69], v[70:71], off offset:288

; __device__ __forceinline__ unsigned cvt_pk_bf16(float lo, float hi) { const cvt2_f32x2 v = {lo, hi}; const cvt2_bf16x2 r = __builtin_convertvector(v, cvt2_bf16x2); return __builtin_bit_cast(unsigned, r); }
;     __device__ __forceinline__ void operator()(const f32x4 (&acc)[2][2][4][2], const Unit& u, int wr, int wc, int fr, int fq) const {
;     ...
;                 const int row = row0 + ai * HALF + m * 16;
;                 const size_t off = (size_t)row * 2048 + col0;
;                 float s = 0.f;
; #pragma unroll
;                 for (int bj = 0; bj < 2; ++bj)
; #pragma unroll
;                     for (int n = 0; n < 2; ++n) {
;                         const f32x4 b = *(const f32x4*)(base + off + bj * HALF + n * 16);
;                         const f32x4 v = b + acc[ai][bj][m][n];
;                         *(f32x4*)(out + off + bj * HALF + n * 16) = v;
;                         if (xb) { u32x2 w; w.x = cvt_pk_bf16(v[0], v[1]); w.y = cvt_pk_bf16(v[2], v[3]); *(u32x2*)(xb + off + bj * HALF + n * 16) = w; }
.LBB0_360:
	v_add_u32_e32 v50, 0x90, v138
	s_waitcnt lgkmcnt(0)
	v_ashrrev_i32_e32 v51, 31, v50
	v_lshlrev_b64 v[52:53], 11, v[50:51]
	v_lshl_add_u64 v[52:53], v[52:53], 0, v[136:137]
	v_lshlrev_b64 v[56:57], 2, v[52:53]
	v_lshl_add_u64 v[54:55], s[12:13], 0, v[56:57]
	global_load_dwordx4 v[58:61], v[54:55], off
	global_load_dwordx4 v[156:159], v[54:55], off offset:64
	global_load_dwordx4 v[160:163], v[54:55], off offset:512
	global_load_dwordx4 v[164:167], v[54:55], off offset:576
	s_and_b64 vcc, exec, s[8:9]
	v_lshl_add_u64 v[56:57], s[26:27], 0, v[56:57]
	v_lshl_add_u64 v[52:53], v[52:53], 1, s[18:19]
	s_waitcnt vmcnt(0)
	v_pk_add_f32 v[48:49], v[48:49], v[60:61]
	v_pk_add_f32 v[46:47], v[46:47], v[58:59]
	global_store_dwordx4 v[56:57], v[46:49], off
	s_cbranch_vccnz .LBB0_362
	v_cvt_pk_bf16_f32 v58, v46, v47
	v_cvt_pk_bf16_f32 v59, v48, v49
	global_store_dwordx2 v[52:53], v[58:59], off
.LBB0_362:
	s_and_b64 vcc, exec, s[8:9]
	v_pk_add_f32 v[44:45], v[44:45], v[158:159]
	v_pk_add_f32 v[42:43], v[42:43], v[156:157]
	global_store_dwordx4 v[56:57], v[42:45], off offset:64
	s_cbranch_vccnz .LBB0_364

; __device__ __forceinline__ unsigned cvt_pk_bf16(float lo, float hi) { const cvt2_f32x2 v = {lo, hi}; const cvt2_bf16x2 r = __builtin_convertvector(v, cvt2_bf16x2); return __builtin_bit_cast(unsigned, r); }
;     __device__ __forceinline__ void operator()(const f32x4 (&acc)[2][2][4][2], const Unit& u, int wr, int wc, int fr, int fq) const {
;     ...
;                 for (int bj = 0; bj < 2; ++bj)
; #pragma unroll
;                     for (int n = 0; n < 2; ++n) {
;                         const f32x4 b = *(const f32x4*)(base + off + bj * HALF + n * 16);
;                         const f32x4 v = b + acc[ai][bj][m][n];
;                         *(f32x4*)(out + off + bj * HALF + n * 16) = v;
;                         if (xb) { u32x2 w; w.x = cvt_pk_bf16(v[0], v[1]); w.y = cvt_pk_bf16(v[2], v[3]); *(u32x2*)(xb + off + bj * HALF + n * 16) = w; }
	v_cvt_pk_bf16_f32 v156, v42, v43
	v_cvt_pk_bf16_f32 v157, v44, v45
	global_store_dwordx2 v[52:53], v[156:157], off offset:32
.LBB0_364:
	s_and_b64 vcc, exec, s[8:9]
	v_pk_add_f32 v[40:41], v[40:41], v[162:163]
	v_pk_add_f32 v[38:39], v[38:39], v[160:161]
	global_store_dwordx4 v[56:57], v[38:41], off offset:512
	s_cbranch_vccnz .LBB0_366

; __device__ __forceinline__ unsigned cvt_pk_bf16(float lo, float hi) { const cvt2_f32x2 v = {lo, hi}; const cvt2_bf16x2 r = __builtin_convertvector(v, cvt2_bf16x2); return __builtin_bit_cast(unsigned, r); }
;     __device__ __forceinline__ void operator()(const f32x4 (&acc)[2][2][4][2], const Unit& u, int wr, int wc, int fr, int fq) const {
;     ...
;                 for (int bj = 0; bj < 2; ++bj)
; #pragma unroll
;                     for (int n = 0; n < 2; ++n) {
;                         const f32x4 b = *(const f32x4*)(base + off + bj * HALF + n * 16);
;                         const f32x4 v = b + acc[ai][bj][m][n];
;                         *(f32x4*)(out + off + bj * HALF + n * 16) = v;
;                         if (xb) { u32x2 w; w.x = cvt_pk_bf16(v[0], v[1]); w.y = cvt_pk_bf16(v[2], v[3]); *(u32x2*)(xb + off + bj * HALF + n * 16) = w; }
	v_cvt_pk_bf16_f32 v160, v38, v39
	v_cvt_pk_bf16_f32 v161, v40, v41
	global_store_dwordx2 v[52:53], v[160:161], off offset:256
.LBB0_366:
	s_and_b64 vcc, exec, s[8:9]
	v_pk_add_f32 v[36:37], v[36:37], v[166:167]
	v_pk_add_f32 v[34:35], v[34:35], v[164:165]
	global_store_dwordx4 v[56:57], v[34:37], off offset:576
	s_cbranch_vccnz .LBB0_368

; __device__ __forceinline__ unsigned cvt_pk_bf16(float lo, float hi) { const cvt2_f32x2 v = {lo, hi}; const cvt2_bf16x2 r = __builtin_convertvector(v, cvt2_bf16x2); return __builtin_bit_cast(unsigned, r); }
;     __device__ __forceinline__ void operator()(const f32x4 (&acc)[2][2][4][2], const Unit& u, int wr, int wc, int fr, int fq) const {
;     ...
;                         if (xb) { u32x2 w; w.x = cvt_pk_bf16(v[0], v[1]); w.y = cvt_pk_bf16(v[2], v[3]); *(u32x2*)(xb + off + bj * HALF + n * 16) = w; }
	v_cvt_pk_bf16_f32 v54, v34, v35
	v_cvt_pk_bf16_f32 v55, v36, v37
	global_store_dwordx2 v[52:53], v[54:55], off offset:288

; __device__ __forceinline__ unsigned cvt_pk_bf16(float lo, float hi) { const cvt2_f32x2 v = {lo, hi}; const cvt2_bf16x2 r = __builtin_convertvector(v, cvt2_bf16x2); return __builtin_bit_cast(unsigned, r); }
;     __device__ __forceinline__ void operator()(const f32x4 (&acc)[2][2][4][2], const Unit& u, int wr, int wc, int fr, int fq) const {
;     ...
;                 const int row = row0 + ai * HALF + m * 16;
;                 const size_t off = (size_t)row * 2048 + col0;
;                 float s = 0.f;
; #pragma unroll
;                 for (int bj = 0; bj < 2; ++bj)
; #pragma unroll
;                     for (int n = 0; n < 2; ++n) {
;                         const f32x4 b = *(const f32x4*)(base + off + bj * HALF + n * 16);
;                         const f32x4 v = b + acc[ai][bj][m][n];
;                         *(f32x4*)(out + off + bj * HALF + n * 16) = v;
;                         if (xb) { u32x2 w; w.x = cvt_pk_bf16(v[0], v[1]); w.y = cvt_pk_bf16(v[2], v[3]); *(u32x2*)(xb + off + bj * HALF + n * 16) = w; }
.LBB0_372:
	v_add_u32_e32 v34, 0xa0, v138
	s_waitcnt lgkmcnt(0)
	v_ashrrev_i32_e32 v35, 31, v34
	v_lshlrev_b64 v[36:37], 11, v[34:35]
	v_lshl_add_u64 v[36:37], v[36:37], 0, v[136:137]
	v_lshlrev_b64 v[40:41], 2, v[36:37]
	v_lshl_add_u64 v[38:39], s[12:13], 0, v[40:41]
	global_load_dwordx4 v[42:45], v[38:39], off
	global_load_dwordx4 v[156:159], v[38:39], off offset:64
	global_load_dwordx4 v[160:163], v[38:39], off offset:512
	global_load_dwordx4 v[164:167], v[38:39], off offset:576
	s_and_b64 vcc, exec, s[8:9]
	v_lshl_add_u64 v[40:41], s[26:27], 0, v[40:41]
	v_lshl_add_u64 v[36:37], v[36:37], 1, s[18:19]
	s_mov_b32 s60, 0x2c000
	s_waitcnt vmcnt(0)
	v_pk_add_f32 v[32:33], v[32:33], v[44:45]
	v_pk_add_f32 v[30:31], v[30:31], v[42:43]
	global_store_dwordx4 v[40:41], v[30:33], off
	s_cbranch_vccnz .LBB0_374
	v_cvt_pk_bf16_f32 v42, v30, v31
	v_cvt_pk_bf16_f32 v43, v32, v33
	global_store_dwordx2 v[36:37], v[42:43], off
.LBB0_374:
	s_and_b64 vcc, exec, s[8:9]
	v_pk_add_f32 v[28:29], v[28:29], v[158:159]
	v_pk_add_f32 v[26:27], v[26:27], v[156:157]
	global_store_dwordx4 v[40:41], v[26:29], off offset:64
	s_cbranch_vccnz .LBB0_376

; __device__ __forceinline__ unsigned cvt_pk_bf16(float lo, float hi) { const cvt2_f32x2 v = {lo, hi}; const cvt2_bf16x2 r = __builtin_convertvector(v, cvt2_bf16x2); return __builtin_bit_cast(unsigned, r); }
;     __device__ __forceinline__ void operator()(const f32x4 (&acc)[2][2][4][2], const Unit& u, int wr, int wc, int fr, int fq) const {
;     ...
;                 for (int bj = 0; bj < 2; ++bj)
; #pragma unroll
;                     for (int n = 0; n < 2; ++n) {
;                         const f32x4 b = *(const f32x4*)(base + off + bj * HALF + n * 16);
;                         const f32x4 v = b + acc[ai][bj][m][n];
;                         *(f32x4*)(out + off + bj * HALF + n * 16) = v;
;                         if (xb) { u32x2 w; w.x = cvt_pk_bf16(v[0], v[1]); w.y = cvt_pk_bf16(v[2], v[3]); *(u32x2*)(xb + off + bj * HALF + n * 16) = w; }
	v_cvt_pk_bf16_f32 v156, v26, v27
	v_cvt_pk_bf16_f32 v157, v28, v29
	global_store_dwordx2 v[36:37], v[156:157], off offset:32
.LBB0_376:
	s_and_b64 vcc, exec, s[8:9]
	v_pk_add_f32 v[24:25], v[24:25], v[162:163]
	v_pk_add_f32 v[22:23], v[22:23], v[160:161]
	global_store_dwordx4 v[40:41], v[22:25], off offset:512
	s_cbranch_vccnz .LBB0_378

; __device__ __forceinline__ unsigned cvt_pk_bf16(float lo, float hi) { const cvt2_f32x2 v = {lo, hi}; const cvt2_bf16x2 r = __builtin_convertvector(v, cvt2_bf16x2); return __builtin_bit_cast(unsigned, r); }
;     __device__ __forceinline__ void operator()(const f32x4 (&acc)[2][2][4][2], const Unit& u, int wr, int wc, int fr, int fq) const {
;     ...
;                 for (int bj = 0; bj < 2; ++bj)
; #pragma unroll
;                     for (int n = 0; n < 2; ++n) {
;                         const f32x4 b = *(const f32x4*)(base + off + bj * HALF + n * 16);
;                         const f32x4 v = b + acc[ai][bj][m][n];
;                         *(f32x4*)(out + off + bj * HALF + n * 16) = v;
;                         if (xb) { u32x2 w; w.x = cvt_pk_bf16(v[0], v[1]); w.y = cvt_pk_bf16(v[2], v[3]); *(u32x2*)(xb + off + bj * HALF + n * 16) = w; }
	v_cvt_pk_bf16_f32 v160, v22, v23
	v_cvt_pk_bf16_f32 v161, v24, v25
	global_store_dwordx2 v[36:37], v[160:161], off offset:256
.LBB0_378:
	s_and_b64 vcc, exec, s[8:9]
	v_pk_add_f32 v[20:21], v[20:21], v[166:167]
	v_pk_add_f32 v[18:19], v[18:19], v[164:165]
	global_store_dwordx4 v[40:41], v[18:21], off offset:576
	s_cbranch_vccnz .LBB0_380

; __device__ __forceinline__ unsigned cvt_pk_bf16(float lo, float hi) { const cvt2_f32x2 v = {lo, hi}; const cvt2_bf16x2 r = __builtin_convertvector(v, cvt2_bf16x2); return __builtin_bit_cast(unsigned, r); }
;     __device__ __forceinline__ void operator()(const f32x4 (&acc)[2][2][4][2], const Unit& u, int wr, int wc, int fr, int fq) const {
;     ...
;                         if (xb) { u32x2 w; w.x = cvt_pk_bf16(v[0], v[1]); w.y = cvt_pk_bf16(v[2], v[3]); *(u32x2*)(xb + off + bj * HALF + n * 16) = w; }
	v_cvt_pk_bf16_f32 v38, v18, v19
	v_cvt_pk_bf16_f32 v39, v20, v21
	global_store_dwordx2 v[36:37], v[38:39], off offset:288

; __device__ __forceinline__ unsigned cvt_pk_bf16(float lo, float hi) { const cvt2_f32x2 v = {lo, hi}; const cvt2_bf16x2 r = __builtin_convertvector(v, cvt2_bf16x2); return __builtin_bit_cast(unsigned, r); }
;     __device__ __forceinline__ void operator()(const f32x4 (&acc)[2][2][4][2], const Unit& u, int wr, int wc, int fr, int fq) const {
;     ...
;                 const int row = row0 + ai * HALF + m * 16;
;                 const size_t off = (size_t)row * 2048 + col0;
;                 float s = 0.f;
; #pragma unroll
;                 for (int bj = 0; bj < 2; ++bj)
; #pragma unroll
;                     for (int n = 0; n < 2; ++n) {
;                         const f32x4 b = *(const f32x4*)(base + off + bj * HALF + n * 16);
;                         const f32x4 v = b + acc[ai][bj][m][n];
;                         *(f32x4*)(out + off + bj * HALF + n * 16) = v;
;                         if (xb) { u32x2 w; w.x = cvt_pk_bf16(v[0], v[1]); w.y = cvt_pk_bf16(v[2], v[3]); *(u32x2*)(xb + off + bj * HALF + n * 16) = w; }
.LBB0_384:
	v_add_u32_e32 v18, 0xb0, v138
	s_waitcnt lgkmcnt(0)
	v_ashrrev_i32_e32 v19, 31, v18
	v_lshlrev_b64 v[20:21], 11, v[18:19]
	v_lshl_add_u64 v[20:21], v[20:21], 0, v[136:137]
	v_lshlrev_b64 v[24:25], 2, v[20:21]
	v_lshl_add_u64 v[22:23], s[12:13], 0, v[24:25]
	global_load_dwordx4 v[26:29], v[22:23], off
	global_load_dwordx4 v[156:159], v[22:23], off offset:64
	global_load_dwordx4 v[160:163], v[22:23], off offset:512
	global_load_dwordx4 v[164:167], v[22:23], off offset:576
	s_and_b64 vcc, exec, s[8:9]
	v_lshl_add_u64 v[24:25], s[26:27], 0, v[24:25]
	v_lshl_add_u64 v[20:21], v[20:21], 1, s[18:19]
	s_waitcnt vmcnt(0)
	v_pk_add_f32 v[16:17], v[16:17], v[28:29]
	v_pk_add_f32 v[14:15], v[14:15], v[26:27]
	global_store_dwordx4 v[24:25], v[14:17], off
	s_cbranch_vccnz .LBB0_386
	v_cvt_pk_bf16_f32 v26, v14, v15
	v_cvt_pk_bf16_f32 v27, v16, v17
	global_store_dwordx2 v[20:21], v[26:27], off
.LBB0_386:
	s_and_b64 vcc, exec, s[8:9]
	v_pk_add_f32 v[12:13], v[12:13], v[158:159]
	v_pk_add_f32 v[10:11], v[10:11], v[156:157]
	global_store_dwordx4 v[24:25], v[10:13], off offset:64
	s_cbranch_vccnz .LBB0_388

; __device__ __forceinline__ unsigned cvt_pk_bf16(float lo, float hi) { const cvt2_f32x2 v = {lo, hi}; const cvt2_bf16x2 r = __builtin_convertvector(v, cvt2_bf16x2); return __builtin_bit_cast(unsigned, r); }
;     __device__ __forceinline__ void operator()(const f32x4 (&acc)[2][2][4][2], const Unit& u, int wr, int wc, int fr, int fq) const {
;     ...
;                 for (int bj = 0; bj < 2; ++bj)
; #pragma unroll
;                     for (int n = 0; n < 2; ++n) {
;                         const f32x4 b = *(const f32x4*)(base + off + bj * HALF + n * 16);
;                         const f32x4 v = b + acc[ai][bj][m][n];
;                         *(f32x4*)(out + off + bj * HALF + n * 16) = v;
;                         if (xb) { u32x2 w; w.x = cvt_pk_bf16(v[0], v[1]); w.y = cvt_pk_bf16(v[2], v[3]); *(u32x2*)(xb + off + bj * HALF + n * 16) = w; }
	v_cvt_pk_bf16_f32 v156, v10, v11
	v_cvt_pk_bf16_f32 v157, v12, v13
	global_store_dwordx2 v[20:21], v[156:157], off offset:32
.LBB0_388:
	s_and_b64 vcc, exec, s[8:9]
	v_pk_add_f32 v[8:9], v[8:9], v[162:163]
	v_pk_add_f32 v[6:7], v[6:7], v[160:161]
	global_store_dwordx4 v[24:25], v[6:9], off offset:512
	s_cbranch_vccnz .LBB0_390

; __device__ __forceinline__ unsigned cvt_pk_bf16(float lo, float hi) { const cvt2_f32x2 v = {lo, hi}; const cvt2_bf16x2 r = __builtin_convertvector(v, cvt2_bf16x2); return __builtin_bit_cast(unsigned, r); }
;     __device__ __forceinline__ void operator()(const f32x4 (&acc)[2][2][4][2], const Unit& u, int wr, int wc, int fr, int fq) const {
;     ...
;                 for (int bj = 0; bj < 2; ++bj)
; #pragma unroll
;                     for (int n = 0; n < 2; ++n) {
;                         const f32x4 b = *(const f32x4*)(base + off + bj * HALF + n * 16);
;                         const f32x4 v = b + acc[ai][bj][m][n];
;                         *(f32x4*)(out + off + bj * HALF + n * 16) = v;
;                         if (xb) { u32x2 w; w.x = cvt_pk_bf16(v[0], v[1]); w.y = cvt_pk_bf16(v[2], v[3]); *(u32x2*)(xb + off + bj * HALF + n * 16) = w; }
	v_cvt_pk_bf16_f32 v160, v6, v7
	v_cvt_pk_bf16_f32 v161, v8, v9
	global_store_dwordx2 v[20:21], v[160:161], off offset:256
.LBB0_390:
	s_and_b64 vcc, exec, s[8:9]
	v_pk_add_f32 v[4:5], v[4:5], v[166:167]
	v_pk_add_f32 v[2:3], v[2:3], v[164:165]
	global_store_dwordx4 v[24:25], v[2:5], off offset:576
	s_cbranch_vccnz .LBB0_392

; __device__ __forceinline__ unsigned cvt_pk_bf16(float lo, float hi) { const cvt2_f32x2 v = {lo, hi}; const cvt2_bf16x2 r = __builtin_convertvector(v, cvt2_bf16x2); return __builtin_bit_cast(unsigned, r); }
;     __device__ __forceinline__ void operator()(const f32x4 (&acc)[2][2][4][2], const Unit& u, int wr, int wc, int fr, int fq) const {
;     ...
;                         if (xb) { u32x2 w; w.x = cvt_pk_bf16(v[0], v[1]); w.y = cvt_pk_bf16(v[2], v[3]); *(u32x2*)(xb + off + bj * HALF + n * 16) = w; }
	v_cvt_pk_bf16_f32 v22, v2, v3
	v_cvt_pk_bf16_f32 v23, v4, v5
	global_store_dwordx2 v[20:21], v[22:23], off offset:288

; __device__ __forceinline__ unsigned cvt_pk_bf16(float lo, float hi) { const cvt2_f32x2 v = {lo, hi}; const cvt2_bf16x2 r = __builtin_convertvector(v, cvt2_bf16x2); return __builtin_bit_cast(unsigned, r); }
;     __device__ __forceinline__ void operator()(const f32x4 (&acc)[2][2][4][2], const Unit& u, int wr, int wc, int fr, int fq) const {
;     ...
;                 const int row = row0 + ai * HALF + m * 16;
;                 const size_t off = (size_t)row * 2048 + col0;
;                 float s = 0.f;
; #pragma unroll
;                 for (int bj = 0; bj < 2; ++bj)
; #pragma unroll
;                     for (int n = 0; n < 2; ++n) {
;                         const f32x4 b = *(const f32x4*)(base + off + bj * HALF + n * 16);
;                         const f32x4 v = b + acc[ai][bj][m][n];
;                         *(f32x4*)(out + off + bj * HALF + n * 16) = v;
;                         if (xb) { u32x2 w; w.x = cvt_pk_bf16(v[0], v[1]); w.y = cvt_pk_bf16(v[2], v[3]); *(u32x2*)(xb + off + bj * HALF + n * 16) = w; }
.LBB0_459:
	v_lshl_add_u32 v138, s35, 8, v146
	v_lshl_or_b32 v136, s34, 8, v148
	v_ashrrev_i32_e32 v139, 31, v138
	v_ashrrev_i32_e32 v137, 31, v136
	v_lshlrev_b64 v[140:141], 11, v[138:139]
	v_lshl_add_u64 v[142:143], v[140:141], 0, v[136:137]
	v_lshlrev_b64 v[144:145], 2, v[142:143]
	v_lshl_add_u64 v[140:141], s[14:15], 0, v[144:145]
	global_load_dwordx4 v[150:153], v[140:141], off
	global_load_dwordx4 v[156:159], v[140:141], off offset:64
	global_load_dwordx4 v[160:163], v[140:141], off offset:512
	global_load_dwordx4 v[164:167], v[140:141], off offset:576
	v_cndmask_b32_e64 v154, 0, 1, s[40:41]
	v_cmp_ne_u32_e64 s[8:9], 1, v154
	s_andn2_b64 vcc, exec, s[40:41]
	v_lshl_add_u64 v[144:145], s[12:13], 0, v[144:145]
	v_lshl_add_u64 v[142:143], v[142:143], 1, s[28:29]
	s_mov_b32 s74, 0x8000
	s_mov_b32 s78, 0xc000
	s_mov_b32 s79, 0x2aaaaaab
	s_mov_b32 s83, 0x30000
	s_mov_b32 s57, 0x28000
	s_mov_b32 s91, 0x6c000
	s_waitcnt vmcnt(0)
	v_pk_add_f32 v[128:129], v[128:129], v[152:153]
	v_pk_add_f32 v[126:127], v[126:127], v[150:151]
	global_store_dwordx4 v[144:145], v[126:129], off
	s_cbranch_vccnz .LBB0_461
	v_cvt_pk_bf16_f32 v150, v126, v127
	v_cvt_pk_bf16_f32 v151, v128, v129
	global_store_dwordx2 v[142:143], v[150:151], off

; __device__ __forceinline__ unsigned cvt_pk_bf16(float lo, float hi) { const cvt2_f32x2 v = {lo, hi}; const cvt2_bf16x2 r = __builtin_convertvector(v, cvt2_bf16x2); return __builtin_bit_cast(unsigned, r); }
;     __device__ __forceinline__ void operator()(const f32x4 (&acc)[2][2][4][2], const Unit& u, int wr, int wc, int fr, int fq) const {
;     ...
;                 const int row = row0 + ai * HALF + m * 16;
;                 const size_t off = (size_t)row * 2048 + col0;
;                 float s = 0.f;
; #pragma unroll
;                 for (int bj = 0; bj < 2; ++bj)
; #pragma unroll
;                     for (int n = 0; n < 2; ++n) {
;                         const f32x4 b = *(const f32x4*)(base + off + bj * HALF + n * 16);
;                         const f32x4 v = b + acc[ai][bj][m][n];
;                         *(f32x4*)(out + off + bj * HALF + n * 16) = v;
;                         if (xb) { u32x2 w; w.x = cvt_pk_bf16(v[0], v[1]); w.y = cvt_pk_bf16(v[2], v[3]); *(u32x2*)(xb + off + bj * HALF + n * 16) = w; }
.LBB0_471:
	v_or_b32_e32 v114, 16, v138
	s_waitcnt lgkmcnt(0)
	v_ashrrev_i32_e32 v115, 31, v114
	v_lshlrev_b64 v[116:117], 11, v[114:115]
	v_lshl_add_u64 v[116:117], v[116:117], 0, v[136:137]
	v_lshlrev_b64 v[120:121], 2, v[116:117]
	v_lshl_add_u64 v[118:119], s[14:15], 0, v[120:121]
	global_load_dwordx4 v[122:125], v[118:119], off
	global_load_dwordx4 v[156:159], v[118:119], off offset:64
	global_load_dwordx4 v[160:163], v[118:119], off offset:512
	global_load_dwordx4 v[164:167], v[118:119], off offset:576
	s_and_b64 vcc, exec, s[8:9]
	v_lshl_add_u64 v[120:121], s[12:13], 0, v[120:121]
	v_lshl_add_u64 v[116:117], v[116:117], 1, s[28:29]
	s_waitcnt vmcnt(0)
	v_pk_add_f32 v[112:113], v[112:113], v[124:125]
	v_pk_add_f32 v[110:111], v[110:111], v[122:123]
	global_store_dwordx4 v[120:121], v[110:113], off
	s_cbranch_vccnz .LBB0_473
	v_cvt_pk_bf16_f32 v122, v110, v111
	v_cvt_pk_bf16_f32 v123, v112, v113
	global_store_dwordx2 v[116:117], v[122:123], off

; __device__ __forceinline__ unsigned cvt_pk_bf16(float lo, float hi) { const cvt2_f32x2 v = {lo, hi}; const cvt2_bf16x2 r = __builtin_convertvector(v, cvt2_bf16x2); return __builtin_bit_cast(unsigned, r); }
;     __device__ __forceinline__ void operator()(const f32x4 (&acc)[2][2][4][2], const Unit& u, int wr, int wc, int fr, int fq) const {
;     ...
;                 const int row = row0 + ai * HALF + m * 16;
;                 const size_t off = (size_t)row * 2048 + col0;
;                 float s = 0.f;
; #pragma unroll
;                 for (int bj = 0; bj < 2; ++bj)
; #pragma unroll
;                     for (int n = 0; n < 2; ++n) {
;                         const f32x4 b = *(const f32x4*)(base + off + bj * HALF + n * 16);
;                         const f32x4 v = b + acc[ai][bj][m][n];
;                         *(f32x4*)(out + off + bj * HALF + n * 16) = v;
;                         if (xb) { u32x2 w; w.x = cvt_pk_bf16(v[0], v[1]); w.y = cvt_pk_bf16(v[2], v[3]); *(u32x2*)(xb + off + bj * HALF + n * 16) = w; }
.LBB0_483:
	v_or_b32_e32 v98, 32, v138
	s_waitcnt lgkmcnt(0)
	v_ashrrev_i32_e32 v99, 31, v98
	v_lshlrev_b64 v[100:101], 11, v[98:99]
	v_lshl_add_u64 v[100:101], v[100:101], 0, v[136:137]
	v_lshlrev_b64 v[104:105], 2, v[100:101]
	v_lshl_add_u64 v[102:103], s[14:15], 0, v[104:105]
	global_load_dwordx4 v[106:109], v[102:103], off
	global_load_dwordx4 v[156:159], v[102:103], off offset:64
	global_load_dwordx4 v[160:163], v[102:103], off offset:512
	global_load_dwordx4 v[164:167], v[102:103], off offset:576
	s_and_b64 vcc, exec, s[8:9]
	v_lshl_add_u64 v[104:105], s[12:13], 0, v[104:105]
	v_lshl_add_u64 v[100:101], v[100:101], 1, s[28:29]
	s_waitcnt vmcnt(0)
	v_pk_add_f32 v[96:97], v[96:97], v[108:109]
	v_pk_add_f32 v[94:95], v[94:95], v[106:107]
	global_store_dwordx4 v[104:105], v[94:97], off
	s_cbranch_vccnz .LBB0_485
	v_cvt_pk_bf16_f32 v106, v94, v95
	v_cvt_pk_bf16_f32 v107, v96, v97
	global_store_dwordx2 v[100:101], v[106:107], off

; __device__ __forceinline__ unsigned cvt_pk_bf16(float lo, float hi) { const cvt2_f32x2 v = {lo, hi}; const cvt2_bf16x2 r = __builtin_convertvector(v, cvt2_bf16x2); return __builtin_bit_cast(unsigned, r); }
;     __device__ __forceinline__ void operator()(const f32x4 (&acc)[2][2][4][2], const Unit& u, int wr, int wc, int fr, int fq) const {
;     ...
;                 const int row = row0 + ai * HALF + m * 16;
;                 const size_t off = (size_t)row * 2048 + col0;
;                 float s = 0.f;
; #pragma unroll
;                 for (int bj = 0; bj < 2; ++bj)
; #pragma unroll
;                     for (int n = 0; n < 2; ++n) {
;                         const f32x4 b = *(const f32x4*)(base + off + bj * HALF + n * 16);
;                         const f32x4 v = b + acc[ai][bj][m][n];
;                         *(f32x4*)(out + off + bj * HALF + n * 16) = v;
;                         if (xb) { u32x2 w; w.x = cvt_pk_bf16(v[0], v[1]); w.y = cvt_pk_bf16(v[2], v[3]); *(u32x2*)(xb + off + bj * HALF + n * 16) = w; }
.LBB0_495:
	v_or_b32_e32 v82, 48, v138
	s_waitcnt lgkmcnt(0)
	v_ashrrev_i32_e32 v83, 31, v82
	v_lshlrev_b64 v[84:85], 11, v[82:83]
	v_lshl_add_u64 v[84:85], v[84:85], 0, v[136:137]
	v_lshlrev_b64 v[88:89], 2, v[84:85]
	v_lshl_add_u64 v[86:87], s[14:15], 0, v[88:89]
	global_load_dwordx4 v[90:93], v[86:87], off
	global_load_dwordx4 v[156:159], v[86:87], off offset:64
	global_load_dwordx4 v[160:163], v[86:87], off offset:512
	global_load_dwordx4 v[164:167], v[86:87], off offset:576
	s_and_b64 vcc, exec, s[8:9]
	v_lshl_add_u64 v[88:89], s[12:13], 0, v[88:89]
	v_lshl_add_u64 v[84:85], v[84:85], 1, s[28:29]
	s_waitcnt vmcnt(0)
	v_pk_add_f32 v[80:81], v[80:81], v[92:93]
	v_pk_add_f32 v[78:79], v[78:79], v[90:91]
	global_store_dwordx4 v[88:89], v[78:81], off
	s_cbranch_vccnz .LBB0_497
	v_cvt_pk_bf16_f32 v90, v78, v79
	v_cvt_pk_bf16_f32 v91, v80, v81
	global_store_dwordx2 v[84:85], v[90:91], off

; __device__ __forceinline__ unsigned cvt_pk_bf16(float lo, float hi) { const cvt2_f32x2 v = {lo, hi}; const cvt2_bf16x2 r = __builtin_convertvector(v, cvt2_bf16x2); return __builtin_bit_cast(unsigned, r); }
;     __device__ __forceinline__ void operator()(const f32x4 (&acc)[2][2][4][2], const Unit& u, int wr, int wc, int fr, int fq) const {
;     ...
;                 const int row = row0 + ai * HALF + m * 16;
;                 const size_t off = (size_t)row * 2048 + col0;
;                 float s = 0.f;
; #pragma unroll
;                 for (int bj = 0; bj < 2; ++bj)
; #pragma unroll
;                     for (int n = 0; n < 2; ++n) {
;                         const f32x4 b = *(const f32x4*)(base + off + bj * HALF + n * 16);
;                         const f32x4 v = b + acc[ai][bj][m][n];
;                         *(f32x4*)(out + off + bj * HALF + n * 16) = v;
;                         if (xb) { u32x2 w; w.x = cvt_pk_bf16(v[0], v[1]); w.y = cvt_pk_bf16(v[2], v[3]); *(u32x2*)(xb + off + bj * HALF + n * 16) = w; }
.LBB0_507:
	v_add_u32_e32 v66, 0x80, v138
	s_waitcnt lgkmcnt(0)
	v_ashrrev_i32_e32 v67, 31, v66
	v_lshlrev_b64 v[68:69], 11, v[66:67]
	v_lshl_add_u64 v[68:69], v[68:69], 0, v[136:137]
	v_lshlrev_b64 v[72:73], 2, v[68:69]
	v_lshl_add_u64 v[70:71], s[14:15], 0, v[72:73]
	global_load_dwordx4 v[74:77], v[70:71], off
	global_load_dwordx4 v[156:159], v[70:71], off offset:64
	global_load_dwordx4 v[160:163], v[70:71], off offset:512
	global_load_dwordx4 v[164:167], v[70:71], off offset:576
	s_and_b64 vcc, exec, s[8:9]
	v_lshl_add_u64 v[72:73], s[12:13], 0, v[72:73]
	v_lshl_add_u64 v[68:69], v[68:69], 1, s[28:29]
	s_waitcnt vmcnt(0)
	v_pk_add_f32 v[64:65], v[64:65], v[76:77]
	v_pk_add_f32 v[62:63], v[62:63], v[74:75]
	global_store_dwordx4 v[72:73], v[62:65], off
	s_cbranch_vccnz .LBB0_509
	v_cvt_pk_bf16_f32 v74, v62, v63
	v_cvt_pk_bf16_f32 v75, v64, v65
	global_store_dwordx2 v[68:69], v[74:75], off

; __device__ __forceinline__ unsigned cvt_pk_bf16(float lo, float hi) { const cvt2_f32x2 v = {lo, hi}; const cvt2_bf16x2 r = __builtin_convertvector(v, cvt2_bf16x2); return __builtin_bit_cast(unsigned, r); }
;     __device__ __forceinline__ void operator()(const f32x4 (&acc)[2][2][4][2], const Unit& u, int wr, int wc, int fr, int fq) const {
;     ...
;                 const int row = row0 + ai * HALF + m * 16;
;                 const size_t off = (size_t)row * 2048 + col0;
;                 float s = 0.f;
; #pragma unroll
;                 for (int bj = 0; bj < 2; ++bj)
; #pragma unroll
;                     for (int n = 0; n < 2; ++n) {
;                         const f32x4 b = *(const f32x4*)(base + off + bj * HALF + n * 16);
;                         const f32x4 v = b + acc[ai][bj][m][n];
;                         *(f32x4*)(out + off + bj * HALF + n * 16) = v;
;                         if (xb) { u32x2 w; w.x = cvt_pk_bf16(v[0], v[1]); w.y = cvt_pk_bf16(v[2], v[3]); *(u32x2*)(xb + off + bj * HALF + n * 16) = w; }
.LBB0_519:
	v_add_u32_e32 v50, 0x90, v138
	s_waitcnt lgkmcnt(0)
	v_ashrrev_i32_e32 v51, 31, v50
	v_lshlrev_b64 v[52:53], 11, v[50:51]
	v_lshl_add_u64 v[52:53], v[52:53], 0, v[136:137]
	v_lshlrev_b64 v[56:57], 2, v[52:53]
	v_lshl_add_u64 v[54:55], s[14:15], 0, v[56:57]
	global_load_dwordx4 v[58:61], v[54:55], off
	global_load_dwordx4 v[156:159], v[54:55], off offset:64
	global_load_dwordx4 v[160:163], v[54:55], off offset:512
	global_load_dwordx4 v[164:167], v[54:55], off offset:576
	s_and_b64 vcc, exec, s[8:9]
	v_lshl_add_u64 v[56:57], s[12:13], 0, v[56:57]
	v_lshl_add_u64 v[52:53], v[52:53], 1, s[28:29]
	s_waitcnt vmcnt(0)
	v_pk_add_f32 v[48:49], v[48:49], v[60:61]
	v_pk_add_f32 v[46:47], v[46:47], v[58:59]
	global_store_dwordx4 v[56:57], v[46:49], off
	s_cbranch_vccnz .LBB0_521
	v_cvt_pk_bf16_f32 v58, v46, v47
	v_cvt_pk_bf16_f32 v59, v48, v49
	global_store_dwordx2 v[52:53], v[58:59], off

; __device__ __forceinline__ unsigned cvt_pk_bf16(float lo, float hi) { const cvt2_f32x2 v = {lo, hi}; const cvt2_bf16x2 r = __builtin_convertvector(v, cvt2_bf16x2); return __builtin_bit_cast(unsigned, r); }
;     __device__ __forceinline__ void operator()(const f32x4 (&acc)[2][2][4][2], const Unit& u, int wr, int wc, int fr, int fq) const {
;     ...
;                 const int row = row0 + ai * HALF + m * 16;
;                 const size_t off = (size_t)row * 2048 + col0;
;                 float s = 0.f;
; #pragma unroll
;                 for (int bj = 0; bj < 2; ++bj)
; #pragma unroll
;                     for (int n = 0; n < 2; ++n) {
;                         const f32x4 b = *(const f32x4*)(base + off + bj * HALF + n * 16);
;                         const f32x4 v = b + acc[ai][bj][m][n];
;                         *(f32x4*)(out + off + bj * HALF + n * 16) = v;
;                         if (xb) { u32x2 w; w.x = cvt_pk_bf16(v[0], v[1]); w.y = cvt_pk_bf16(v[2], v[3]); *(u32x2*)(xb + off + bj * HALF + n * 16) = w; }
.LBB0_531:
	v_add_u32_e32 v34, 0xa0, v138
	s_waitcnt lgkmcnt(0)
	v_ashrrev_i32_e32 v35, 31, v34
	v_lshlrev_b64 v[36:37], 11, v[34:35]
	v_lshl_add_u64 v[36:37], v[36:37], 0, v[136:137]
	v_lshlrev_b64 v[40:41], 2, v[36:37]
	v_lshl_add_u64 v[38:39], s[14:15], 0, v[40:41]
	global_load_dwordx4 v[42:45], v[38:39], off
	global_load_dwordx4 v[156:159], v[38:39], off offset:64
	global_load_dwordx4 v[160:163], v[38:39], off offset:512
	global_load_dwordx4 v[164:167], v[38:39], off offset:576
	s_and_b64 vcc, exec, s[8:9]
	v_lshl_add_u64 v[40:41], s[12:13], 0, v[40:41]
	v_lshl_add_u64 v[36:37], v[36:37], 1, s[28:29]
	s_waitcnt vmcnt(0)
	v_pk_add_f32 v[32:33], v[32:33], v[44:45]
	v_pk_add_f32 v[30:31], v[30:31], v[42:43]
	global_store_dwordx4 v[40:41], v[30:33], off
	s_cbranch_vccnz .LBB0_533
	v_cvt_pk_bf16_f32 v42, v30, v31
	v_cvt_pk_bf16_f32 v43, v32, v33
	global_store_dwordx2 v[36:37], v[42:43], off

; __device__ __forceinline__ unsigned cvt_pk_bf16(float lo, float hi) { const cvt2_f32x2 v = {lo, hi}; const cvt2_bf16x2 r = __builtin_convertvector(v, cvt2_bf16x2); return __builtin_bit_cast(unsigned, r); }
;     __device__ __forceinline__ void operator()(const f32x4 (&acc)[2][2][4][2], const Unit& u, int wr, int wc, int fr, int fq) const {
;     ...
;                 const int row = row0 + ai * HALF + m * 16;
;                 const size_t off = (size_t)row * 2048 + col0;
;                 float s = 0.f;
; #pragma unroll
;                 for (int bj = 0; bj < 2; ++bj)
; #pragma unroll
;                     for (int n = 0; n < 2; ++n) {
;                         const f32x4 b = *(const f32x4*)(base + off + bj * HALF + n * 16);
;                         const f32x4 v = b + acc[ai][bj][m][n];
;                         *(f32x4*)(out + off + bj * HALF + n * 16) = v;
;                         if (xb) { u32x2 w; w.x = cvt_pk_bf16(v[0], v[1]); w.y = cvt_pk_bf16(v[2], v[3]); *(u32x2*)(xb + off + bj * HALF + n * 16) = w; }
.LBB0_543:
	v_add_u32_e32 v18, 0xb0, v138
	s_waitcnt lgkmcnt(0)
	v_ashrrev_i32_e32 v19, 31, v18
	v_lshlrev_b64 v[20:21], 11, v[18:19]
	v_lshl_add_u64 v[20:21], v[20:21], 0, v[136:137]
	v_lshlrev_b64 v[24:25], 2, v[20:21]
	v_lshl_add_u64 v[22:23], s[14:15], 0, v[24:25]
	global_load_dwordx4 v[26:29], v[22:23], off
	global_load_dwordx4 v[156:159], v[22:23], off offset:64
	global_load_dwordx4 v[160:163], v[22:23], off offset:512
	global_load_dwordx4 v[164:167], v[22:23], off offset:576
	s_and_b64 vcc, exec, s[8:9]
	v_lshl_add_u64 v[24:25], s[12:13], 0, v[24:25]
	v_lshl_add_u64 v[20:21], v[20:21], 1, s[28:29]
	s_waitcnt vmcnt(0)
	v_pk_add_f32 v[16:17], v[16:17], v[28:29]
	v_pk_add_f32 v[14:15], v[14:15], v[26:27]
	global_store_dwordx4 v[24:25], v[14:17], off
	s_cbranch_vccnz .LBB0_545
	v_cvt_pk_bf16_f32 v26, v14, v15
	v_cvt_pk_bf16_f32 v27, v16, v17
	global_store_dwordx2 v[20:21], v[26:27], off
